# out-proj context half-tile loop: scalar-side DMA addressing, DMA pieces behind MFMAs
# speedup vs baseline: 1.0045x; 1.0045x over previous
; DI int otid() { int t = threadIdx.x; asm volatile("" : "+v"(t)); return t; }
; #define G_ISSUE(ks_, buf_) do { \
;     const bf16_t* wq_ = wp + (ks_) * wks; const bf16_t* xq_ = xp + (ks_) * xks; char* lb_ = ld + (buf_) * STAGE; \
;     dma16(wq_, lb_); dma16(wq_ + 2048, lb_ + 4096); \
;     _Pragma("unroll") for (int i_ = 0; i_ < TJ; ++i_) dma16(xq_ + i_ * 2048, lb_ + 8192 + i_ * 4096); } while (0)
; template <bool VMODE, int TJ>
; DI void gemm_mainloop(const bf16_t* __restrict__ W, const bf16_t* __restrict__ X, int NW, char* smem, f32x16 (&acc)[2][TJ]) {
;     constexpr int XROWS = 64 * TJ, STAGE = (128 + XROWS) * 64, NPW = 2 + TJ;
;     const int tid = otid(), lane = tid & 63, wave = tid >> 6, r = lane & 31, h = lane >> 5, wf = wave & 1, wt = wave >> 1;
;     const int goff = (16 * wave + (lane >> 2)) * 32 + (((lane & 3) ^ (lane >> 4)) << 3);
;     const bf16_t* wp = W + goff;
;     const bf16_t* xp = X + goff;
;     const size_t wks = (size_t)NW * 32, xks = (size_t)NTOK * 32;
;     char* ld = smem + tid * 16;
;     ...
;     const int xr = (r >> 2) & 3;
;     const int fo0 = r * 64 + (((0 + h) ^ xr) << 4), fo1 = r * 64 + (((2 + h) ^ xr) << 4);
;     __syncthreads();
;     ...
;     if (TJ <= 2) {
;         constexpr int NSL = (TJ == 1) ? 6 : 4;
;         G_ISSUE(0, 0);
;         G_ISSUE(1, 1);
;         if (TJ == 1) { G_ISSUE(2, 2); G_ISSUE(3, 3); }
;         int sl = 0;
; template <int TJ>
; DI void outproj_tile(const Params& p, int l, char* smem, int b, int trow0, int n0) {
;     const int tid = otid(), lane = tid & 63, wave = tid >> 6, r = lane & 31, h = lane >> 5, wf = wave & 1, wt = wave >> 1;
;     const bf16_t* W = p.wtout + (size_t)l * D * D + (size_t)n0 * 32;
;     const bf16_t* X = p.hmix + ((size_t)b * TPB + trow0) * 32;
;     f32x16 acc[2][TJ];
;     zero_acc<TJ>(acc);
;     gemm_mainloop<false, TJ>(W, X, D, smem, acc);
.LBB0_52:
	v_readlane_b32 s4, v254, 15
	v_readlane_b32 s5, v254, 16
	s_and_b64 s[4:5], s[4:5], s[48:49]
	s_and_b64 vcc, exec, s[4:5]
	s_cbranch_vccz .LBB0_68
	v_mov_b32_e32 v40, v200
	v_mov_b32_e32 v8, v200
	v_readlane_b32 s4, v254, 17
	v_bfe_u32 v1, v8, 4, 2
	v_bitop3_b32 v1, v1, v8, 3 bitop3:0x78
	s_add_u32 s4, s8, s4
	v_lshlrev_b32_e32 v0, 3, v8
	v_lshlrev_b32_e32 v1, 3, v1
	s_movk_i32 s8, 0xffe0
	s_addc_u32 s5, s9, 0
	v_readlane_b32 s6, v255, 25
	v_and_or_b32 v0, v0, s8, v1
	s_add_u32 s6, s56, s6
	v_ashrrev_i32_e32 v1, 31, v0
	v_lshlrev_b32_e32 v9, 4, v8
	s_addc_u32 s7, s57, 0
	v_lshlrev_b64 v[32:33], 1, v[0:1]
	v_add_u32_e32 v34, 32, v9
	v_lshl_add_u64 v[2:3], s[6:7], 0, v[32:33]
	v_readfirstlane_b32 s6, v34
	v_add_u32_e32 v6, 0x1000, v34
	v_lshl_add_u64 v[0:1], s[4:5], 0, v[32:33]
	s_mov_b32 m0, s6
	v_readfirstlane_b32 s6, v6
	s_barrier
	global_load_lds_dwordx4 v[0:1], off
	v_lshl_add_u64 v[4:5], v[0:1], 0, s[26:27]
	s_mov_b32 m0, s6
	v_add_u32_e32 v10, 0x3000, v34
	global_load_lds_dwordx4 v[4:5], off
	v_add_u32_e32 v4, 0x2000, v34
	v_mov_b32_e32 v16, 0
	v_readfirstlane_b32 s6, v4
	s_mov_b32 m0, s6
	s_mov_b64 s[6:7], 0x10000
	v_lshl_add_u64 v[4:5], v[0:1], 0, s[6:7]
	s_mov_b64 s[6:7], 0x120000
	v_lshl_add_u64 v[6:7], v[2:3], 0, s[6:7]
	v_readfirstlane_b32 s6, v10
	global_load_lds_dwordx4 v[2:3], off
	s_mov_b32 m0, s6
	s_mov_b64 s[6:7], 0x11000
	v_add_u32_e32 v10, 0x4000, v34
	global_load_lds_dwordx4 v[4:5], off
	v_lshl_add_u64 v[4:5], v[0:1], 0, s[6:7]
	v_readfirstlane_b32 s6, v10
	s_mov_b32 m0, s6
	v_add_u32_e32 v10, 0x6000, v34
	global_load_lds_dwordx4 v[4:5], off
	v_add_u32_e32 v4, 0x5000, v34
	v_and_b32_e32 v37, 0xfffff800, v9
	v_readfirstlane_b32 s6, v4
	s_mov_b32 m0, s6
	v_readfirstlane_b32 s6, v10
	v_add_u32_e32 v10, 0x7000, v34
	global_load_lds_dwordx4 v[6:7], off
	v_lshl_add_u64 v[4:5], v[0:1], 0, s[76:77]
	s_mov_b32 m0, s6
	v_readfirstlane_b32 s6, v10
	global_load_lds_dwordx4 v[4:5], off
	v_lshl_add_u64 v[4:5], v[0:1], 0, s[14:15]
	s_mov_b32 m0, s6
	v_lshl_add_u64 v[6:7], v[2:3], 0, s[84:85]
	global_load_lds_dwordx4 v[4:5], off
	v_add_u32_e32 v4, 0x8000, v34
	v_lshl_add_u64 v[2:3], v[2:3], 0, s[24:25]
	v_readfirstlane_b32 s6, v4
	s_mov_b32 m0, s6
	v_lshl_add_u64 v[4:5], v[0:1], 0, s[10:11]
	global_load_lds_dwordx4 v[6:7], off
	v_add_u32_e32 v6, 0x9000, v34
	v_lshl_add_u64 v[0:1], v[0:1], 0, s[38:39]
	v_readfirstlane_b32 s6, v6
	s_mov_b32 m0, s6
	s_mov_b32 s9, 0
	global_load_lds_dwordx4 v[4:5], off
	v_add_u32_e32 v4, 0xa000, v34
	s_mov_b32 s8, 14
	v_readfirstlane_b32 s6, v4
	s_mov_b32 m0, s6
	v_mov_b32_e32 v17, v16
	global_load_lds_dwordx4 v[0:1], off
	v_add_u32_e32 v0, 0xb000, v34
	v_lshrrev_b32_e32 v1, 2, v8
	v_readfirstlane_b32 s6, v0
	s_mov_b32 m0, s6
	v_bfe_u32 v0, v8, 5, 1
	global_load_lds_dwordx4 v[2:3], off
	v_bfe_u32 v2, v8, 2, 2
	v_lshlrev_b32_e32 v3, 6, v8
	v_readlane_b32 s6, v255, 24
	v_and_b32_e32 v4, 0x7c0, v3
	v_bitop3_b32 v1, v0, v1, 3 bitop3:0x78
	v_bitop3_b32 v0, v0, v2, 2 bitop3:0x36
	s_add_u32 s6, s56, s6
	v_lshl_or_b32 v36, v1, 4, v4
	v_lshl_or_b32 v35, v0, 4, v4
	v_and_b32_e32 v38, 0x1000, v3
	s_addc_u32 s7, s57, 0
	v_mov_b32_e32 v18, v16
	v_mov_b32_e32 v19, v16
	v_mov_b32_e32 v20, v16
	v_mov_b32_e32 v21, v16
	v_mov_b32_e32 v22, v16
	v_mov_b32_e32 v23, v16
	v_mov_b32_e32 v24, v16
	v_mov_b32_e32 v25, v16
	v_mov_b32_e32 v26, v16
	v_mov_b32_e32 v27, v16
	v_mov_b32_e32 v28, v16
	v_mov_b32_e32 v29, v16
	v_mov_b32_e32 v30, v16
	v_mov_b32_e32 v31, v16
	v_mov_b32_e32 v0, v16
	v_mov_b32_e32 v1, v16
	v_mov_b32_e32 v2, v16
	v_mov_b32_e32 v3, v16
	v_mov_b32_e32 v4, v16
	v_mov_b32_e32 v5, v16
	v_mov_b32_e32 v6, v16
	v_mov_b32_e32 v7, v16
	v_mov_b32_e32 v8, v16
	v_mov_b32_e32 v9, v16
	v_mov_b32_e32 v10, v16
	v_mov_b32_e32 v11, v16
	v_mov_b32_e32 v12, v16
	v_mov_b32_e32 v13, v16
	v_mov_b32_e32 v14, v16
	v_mov_b32_e32 v15, v16
	v_readfirstlane_b32 s100, v34
	v_add_u32_e32 v88, 0x20000, v32
	v_add_u32_e32 v89, 0x21000, v32
	v_add_u32_e32 v90, 0x240000, v32
	v_add_u32_e32 v91, 0x30000, v32
	v_add_u32_e32 v92, 0x31000, v32
	v_add_u32_e32 v93, 0x360000, v32
; #define MFMA(a, b, c) __builtin_amdgcn_mfma_f32_32x32x16_bf16((a), (b), (c), 0, 0, 0)
; template <bool VMODE, int TJ>
; DI void gemm_mainloop(const bf16_t* __restrict__ W, const bf16_t* __restrict__ X, int NW, char* smem, f32x16 (&acc)[2][TJ]) {
;     ...
;         for (int kp = 0; kp < 16; ++kp) {
;             if (TJ == 1 && kp + 1 < 16) asm volatile("s_waitcnt vmcnt(6)" ::: "memory");
;             else asm volatile("s_waitcnt vmcnt(0)" ::: "memory");
;             __builtin_amdgcn_s_barrier();
;             const int sn2 = (TJ == 1) ? ((sl + 4 >= NSL) ? sl + 4 - NSL : sl + 4) : 2 - sl;
;             {
;                 const char* sw = smem + sl * STAGE + wf * 64 * 64;
;                 const char* sx = smem + sl * STAGE + 8192 + wt * (32 * TJ) * 64;
;                 bf16x8 fw[2], fx[TJ];
; #pragma unroll
;                 for (int i = 0; i < 2; ++i) fw[i] = *(const bf16x8*)(sw + i * 32 * 64 + fo0);
; #pragma unroll
;                 for (int j = 0; j < TJ; ++j) fx[j] = *(const bf16x8*)(sx + j * 32 * 64 + fo0);
;                 __builtin_amdgcn_sched_barrier(0);
;                 if (TJ == 1) { if (kp + 2 < 16) { G_ISSUE(2 * kp + 4, sn2); G_ISSUE(2 * kp + 5, sn2 + 1); } }
;                 else if (kp + 1 < 16) { G_ISSUE(2 * kp + 2, sn2); G_ISSUE(2 * kp + 3, sn2 + 1); }
;                 __builtin_amdgcn_sched_barrier(0);
; #pragma unroll
;                 for (int i = 0; i < 2; ++i)
; #pragma unroll
;                     for (int j = 0; j < TJ; ++j) acc[i][j] = VMODE ? MFMA(fx[j], fw[i], acc[i][j]) : MFMA(fw[i], fx[j], acc[i][j]);
; #pragma unroll
;                 for (int i = 0; i < 2; ++i) fw[i] = *(const bf16x8*)(sw + i * 32 * 64 + fo1);
; #pragma unroll
;                 for (int j = 0; j < TJ; ++j) fx[j] = *(const bf16x8*)(sx + j * 32 * 64 + fo1);
; #pragma unroll
;                 for (int i = 0; i < 2; ++i)
; #pragma unroll
;                     for (int j = 0; j < TJ; ++j) acc[i][j] = VMODE ? MFMA(fx[j], fw[i], acc[i][j]) : MFMA(fw[i], fx[j], acc[i][j]);
;             }
;             G_COMPUTE(sl + 1);
;             sl = (sl + 2 >= NSL) ? 0 : sl + 2;
;         }
.LBB0_54:
	s_mul_i32 s28, s9, 0x3000
	s_add_i32 s28, s28, 32
	v_add_u32_e32 v39, s28, v38
	v_add_u32_e32 v41, v39, v36
	v_add_u32_e32 v62, s28, v37
	s_waitcnt vmcnt(6)
	s_barrier
	ds_read_b128 v[42:45], v41
	ds_read_b128 v[46:49], v41 offset:2048
	v_add_u32_e32 v63, v62, v36
	ds_read_b128 v[50:53], v63 offset:8192
	s_cmp_gt_i32 s9, 1
	s_cselect_b32 s28, -2, 4
	s_add_i32 s34, s28, s9
	s_mulk_i32 s34, 0x3000
	s_add_i32 s101, s34, s100
	v_add_u32_e32 v39, v39, v35
	v_add_u32_e32 v54, v62, v35
	s_add_i32 s28, s9, 2
	s_cmp_lt_i32 s9, 4
	s_cselect_b32 s9, s28, 0
	s_add_u32 s6, s6, 0x240000
	s_addc_u32 s7, s7, 0
	s_add_u32 s4, s4, 0x20000
	s_addc_u32 s5, s5, 0
	s_add_i32 s8, s8, -1
	s_mov_b32 m0, s101
	s_waitcnt lgkmcnt(0)
	v_mfma_f32_32x32x16_bf16 v[16:31], v[42:45], v[50:53], v[16:31]
	global_load_lds_dwordx4 v88, s[4:5]
	s_add_u32 m0, s101, 0x1000
	v_mfma_f32_32x32x16_bf16 v[0:15], v[46:49], v[50:53], v[0:15]
	global_load_lds_dwordx4 v89, s[4:5]
	s_add_u32 m0, s101, 0x2000
	ds_read_b128 v[42:45], v39
	ds_read_b128 v[46:49], v39 offset:2048
	ds_read_b128 v[50:53], v54 offset:8192
	s_waitcnt lgkmcnt(0)
	v_mfma_f32_32x32x16_bf16 v[16:31], v[42:45], v[50:53], v[16:31]
	global_load_lds_dwordx4 v90, s[6:7]
	s_add_u32 m0, s101, 0x3000
	v_mfma_f32_32x32x16_bf16 v[0:15], v[46:49], v[50:53], v[0:15]
	global_load_lds_dwordx4 v91, s[4:5]
	s_add_u32 m0, s101, 0x4000
	ds_read_b128 v[42:45], v41 offset:12288
	ds_read_b128 v[46:49], v41 offset:14336
	ds_read_b128 v[50:53], v63 offset:20480
	s_waitcnt lgkmcnt(0)
	v_mfma_f32_32x32x16_bf16 v[16:31], v[42:45], v[50:53], v[16:31]
	global_load_lds_dwordx4 v92, s[4:5]
	s_add_u32 m0, s101, 0x5000
	v_mfma_f32_32x32x16_bf16 v[0:15], v[46:49], v[50:53], v[0:15]
	global_load_lds_dwordx4 v93, s[6:7]
	ds_read_b128 v[42:45], v39 offset:12288
	ds_read_b128 v[46:49], v39 offset:14336
	ds_read_b128 v[50:53], v54 offset:20480
	s_waitcnt lgkmcnt(0)
	v_mfma_f32_32x32x16_bf16 v[16:31], v[42:45], v[50:53], v[16:31]
	v_mfma_f32_32x32x16_bf16 v[0:15], v[46:49], v[50:53], v[0:15]
	s_cmp_lg_u32 s8, 0
	s_cbranch_scc1 .LBB0_54
	v_add_u32_e32 v32, 32, v38
	v_add_u32_e32 v41, v32, v36
	v_add_u32_e32 v33, 32, v37
	s_waitcnt vmcnt(6)
	s_barrier
	ds_read_b128 v[42:45], v41 offset:49152
	ds_read_b128 v[46:49], v41 offset:51200
	v_add_u32_e32 v54, v33, v36
	ds_read_b128 v[50:53], v54 offset:57344
	s_waitcnt lgkmcnt(0)
	v_mfma_f32_32x32x16_bf16 v[16:31], v[42:45], v[50:53], v[16:31]
	v_add_u32_e32 v55, v32, v35
	v_add_u32_e32 v56, v33, v35
	v_readlane_b32 s4, v255, 29
	s_nop 1
	v_add_u32_e32 v32, s4, v37
	v_add_u32_e32 v33, v32, v36
	v_mfma_f32_32x32x16_bf16 v[0:15], v[46:49], v[50:53], v[0:15]
	ds_read_b128 v[42:45], v55 offset:49152
	ds_read_b128 v[46:49], v55 offset:51200
	ds_read_b128 v[50:53], v56 offset:57344
	v_add_u32_e32 v32, v32, v35
	s_waitcnt lgkmcnt(0)
	v_mfma_f32_32x32x16_bf16 v[16:31], v[42:45], v[50:53], v[16:31]
	v_mfma_f32_32x32x16_bf16 v[0:15], v[46:49], v[50:53], v[0:15]
	ds_read_b128 v[42:45], v41 offset:61440
	ds_read_b128 v[46:49], v41 offset:63488
	ds_read_b128 v[36:39], v33
	s_waitcnt lgkmcnt(0)
	v_mfma_f32_32x32x16_bf16 v[16:31], v[42:45], v[36:39], v[16:31]
	v_mfma_f32_32x32x16_bf16 v[0:15], v[46:49], v[36:39], v[0:15]
	ds_read_b128 v[36:39], v55 offset:61440
	ds_read_b128 v[42:45], v55 offset:63488
	ds_read_b128 v[32:35], v32
	s_waitcnt vmcnt(0)
	s_barrier
	s_waitcnt lgkmcnt(0)
	v_mfma_f32_32x32x16_bf16 v[16:31], v[36:39], v[32:35], v[16:31]
	v_mfma_f32_32x32x16_bf16 v[0:15], v[42:45], v[32:35], v[0:15]
	ds_read_b128 v[32:35], v41
	ds_read_b128 v[36:39], v41 offset:2048
	ds_read_b128 v[42:45], v54 offset:8192
	s_waitcnt lgkmcnt(0)
	v_mfma_f32_32x32x16_bf16 v[16:31], v[32:35], v[42:45], v[16:31]
	v_readlane_b32 s4, v254, 18
	s_and_b64 vcc, exec, s[50:51]
	v_mfma_f32_32x32x16_bf16 v[0:15], v[36:39], v[42:45], v[0:15]
	ds_read_b128 v[32:35], v55
	ds_read_b128 v[36:39], v55 offset:2048
	ds_read_b128 v[42:45], v56 offset:8192
	s_waitcnt lgkmcnt(0)
	v_mfma_f32_32x32x16_bf16 v[16:31], v[32:35], v[42:45], v[16:31]
	v_mfma_f32_32x32x16_bf16 v[0:15], v[36:39], v[42:45], v[0:15]
	ds_read_b128 v[32:35], v41 offset:12288
	ds_read_b128 v[36:39], v41 offset:14336
	ds_read_b128 v[42:45], v54 offset:20480
	s_waitcnt lgkmcnt(0)
	v_mfma_f32_32x32x16_bf16 v[16:31], v[32:35], v[42:45], v[16:31]
	v_mfma_f32_32x32x16_bf16 v[0:15], v[36:39], v[42:45], v[0:15]
	ds_read_b128 v[32:35], v55 offset:12288
	ds_read_b128 v[36:39], v55 offset:14336
	ds_read_b128 v[42:45], v56 offset:20480
	s_waitcnt vmcnt(0) lgkmcnt(0)
	s_barrier
	v_mfma_f32_32x32x16_bf16 v[16:31], v[32:35], v[42:45], v[16:31]
	v_ashrrev_i32_e32 v32, 2, v40
	v_and_b32_e32 v32, 0xffffffe0, v32
	v_add_u32_e32 v32, s4, v32
	v_cmp_gt_i32_e64 s[40:41], s61, v32
	v_cmp_lt_i32_e64 s[42:43], s21, v32
	s_mov_b64 s[4:5], -1
	v_mfma_f32_32x32x16_bf16 v[0:15], v[36:39], v[42:45], v[0:15]
	s_cbranch_vccz .LBB0_61
	s_and_saveexec_b64 s[4:5], s[42:43]
	s_xor_b64 s[4:5], exec, s[4:5]
	s_cbranch_execz .LBB0_58
	v_readlane_b32 s6, v255, 19
	v_add_u32_e32 v192, 0xfffff800, v32
	v_readlane_b32 s7, v255, 20
	s_add_u32 s6, s46, s6
	s_addc_u32 s7, s47, 0
	v_mov_b64_e32 v[36:37], v[192:193]
